# flat barrier release poll: s_sleep 1 -> s_sleep 6 between polls (fewer requests queued on the release word's memory channel)
# speedup vs baseline: 1.0118x; 1.0118x over previous
.LBB0_143:
	s_and_b32 s1, s0, 0xff
	s_mov_b64 s[4:5], -1
	s_cmp_lg_u32 s1, 0
	s_mov_b64 s[24:25], -1
	s_sleep 6
	s_cbranch_scc0 .LBB0_146
	s_and_b64 vcc, exec, s[24:25]
	s_cbranch_vccz .LBB0_142

.LBB0_534:
	s_and_b32 s1, s0, 0xff
	s_mov_b64 s[4:5], -1
	s_cmp_lg_u32 s1, 0
	s_mov_b64 s[10:11], -1
	s_sleep 6
	s_cbranch_scc0 .LBB0_537
	s_and_b64 vcc, exec, s[10:11]
	s_cbranch_vccz .LBB0_533
